# dk192 tile body: LDS-DMA issue kept at the tile top (dk64 keeps it behind QK)
# speedup vs baseline: 1.0079x; 1.0072x over previous
; #define LAS __attribute__((address_space(3)))
; template <int DK>
; DI void attn_pass(const AttnSrc& s, const int q0, const float sc, LAS unsigned char* lds, f32x16 (&O)[4]) {
;     ...
;     __builtin_amdgcn_s_barrier();
;     asm volatile("" ::: "memory");
;     if (t + DPF < NT) issue(t + DPF, pbuf);
;     if (64 * t <= qw0 + 31) {
;       LAS unsigned char* Kb = lds + buf * STG; LAS unsigned char* Vb = lds + buf * STG + KSZ;
;       f32x16 p0, p1;
;       constexpr int GS = (DK == 64) ? 4 : 2, NG = NS / GS;
;       bf16x8 kfa[2][GS], kfb[2][GS];
;       auto kload = [&](int g, int slot) {
; #pragma unroll
;         for (int j = 0; j < GS; ++j) { const int lc = 2 * (g * GS + j) + h; const int ph = (DK == 64) ? (lc ^ kx) : ((lc & ~7) | ((lc & 7) ^ kx));
;           kfa[slot][j] = *(const LAS bf16x8*)(Kb + krow + ph * 16); kfb[slot][j] = *(const LAS bf16x8*)(Kb + krow + 32 * ROWB + ph * 16); }
;       };
;       kload(0, 0);
; #pragma unroll
;       for (int g = 0; g < NG; ++g) {
;         if (g + 1 < NG) kload(g + 1, (g + 1) & 1);
;         __builtin_amdgcn_s_setprio(1);
; #pragma unroll
;         for (int j = 0; j < GS; ++j) {
;           if (g == 0 && j == 0) {
;             if (REL) {
;               p0 = __builtin_amdgcn_mfma_f32_32x32x16_bf16(kfa[0][0], qf[0], negm, 0, 0, 0);
;               p1 = __builtin_amdgcn_mfma_f32_32x32x16_bf16(kfb[0][0], qf[0], negm, 0, 0, 0);
;             } else {
;               f32x16 z;
; #pragma unroll
;               for (int jj = 0; jj < 16; ++jj) z[jj] = 0.f;
;               p0 = __builtin_amdgcn_mfma_f32_32x32x16_bf16(kfa[0][0], qf[0], z, 0, 0, 0);
;               p1 = __builtin_amdgcn_mfma_f32_32x32x16_bf16(kfb[0][0], qf[0], z, 0, 0, 0);
;             }
;           } else {
;             p0 = __builtin_amdgcn_mfma_f32_32x32x16_bf16(kfa[g & 1][j], qf[g * GS + j], p0, 0, 0, 0);
;             p1 = __builtin_amdgcn_mfma_f32_32x32x16_bf16(kfb[g & 1][j], qf[g * GS + j], p1, 0, 0, 0);
;           }
;         }
;         __builtin_amdgcn_s_setprio(0);
;       }
;       bf16x8 vf[2][4];
;       auto vload = [&](int vt, int slot) {
;         const int vcol = vrow + ((vt ^ vx) << 6);
; #pragma unroll
;         for (int ks = 0; ks < 4; ++ks) {
;           const s16x4 lo = __builtin_bit_cast(s16x4, __builtin_amdgcn_ds_read_tr16_b64_v4i16((LAS s16x4*)(Vb + vcol + ks * 16 * 256)));
.Ln192_top:
	s_sub_i32 s15, s55, 63
	s_cmp_gt_i32 s15, s53
	s_cbranch_scc0 .Ln192_act
	s_branch .LBB0_137
.Ln192_act:
	s_mul_i32 s15, s54, 0xa000
	s_add_i32 s15, s15, 0
	v_add_u32_e32 v0, s15, v204
	v_add_u32_e32 v238, v0, v209
	v_add_u32_e32 v239, v0, v210
	v_add_u32_e32 v240, v0, v213
	v_add_u32_e32 v0, v0, v214
	ds_read_b128 v[66:69], v238
	ds_read_b128 v[70:73], v238 offset:12288
	ds_read_b128 v[146:149], v239
	ds_read_b128 v[150:153], v239 offset:12288
	ds_read_b128 v[154:157], v240
	ds_read_b128 v[158:161], v240 offset:12288
	ds_read_b128 v[220:223], v0
	ds_read_b128 v[224:227], v0 offset:12288
	s_setprio 1
	s_waitcnt lgkmcnt(7)
	v_mfma_f32_32x32x16_bf16 v[82:97], v[66:69], v[98:101], 0
	s_waitcnt lgkmcnt(6)
	v_mfma_f32_32x32x16_bf16 v[66:81], v[70:73], v[98:101], 0
	s_waitcnt lgkmcnt(5)
	v_mfma_f32_32x32x16_bf16 v[82:97], v[146:149], v[102:105], v[82:97]
	s_waitcnt lgkmcnt(4)
	v_mfma_f32_32x32x16_bf16 v[66:81], v[150:153], v[102:105], v[66:81]
	s_setprio 0
	ds_read_b128 v[146:149], v239 offset:128
	ds_read_b128 v[150:153], v239 offset:12416
	ds_read_b128 v[230:233], v238 offset:12416
	ds_read_b128 v[234:237], v238 offset:128
	s_setprio 1
	s_waitcnt lgkmcnt(7)
	v_mfma_f32_32x32x16_bf16 v[82:97], v[154:157], v[106:109], v[82:97]
	s_waitcnt lgkmcnt(6)
	v_mfma_f32_32x32x16_bf16 v[66:81], v[158:161], v[106:109], v[66:81]
	s_waitcnt lgkmcnt(5)
	v_mfma_f32_32x32x16_bf16 v[82:97], v[220:223], v[110:113], v[82:97]
	s_waitcnt lgkmcnt(4)
	v_mfma_f32_32x32x16_bf16 v[66:81], v[224:227], v[110:113], v[66:81]
	s_setprio 0
	ds_read_b128 v[154:157], v240 offset:128
	ds_read_b128 v[158:161], v240 offset:12416
	ds_read_b128 v[220:223], v0 offset:128
	ds_read_b128 v[224:227], v0 offset:12416
	s_setprio 1
	s_waitcnt lgkmcnt(4)
	v_mfma_f32_32x32x16_bf16 v[82:97], v[234:237], v[114:117], v[82:97]
	v_mfma_f32_32x32x16_bf16 v[66:81], v[230:233], v[114:117], v[66:81]
	v_mfma_f32_32x32x16_bf16 v[82:97], v[146:149], v[118:121], v[82:97]
	v_mfma_f32_32x32x16_bf16 v[66:81], v[150:153], v[118:121], v[66:81]
	s_setprio 0
	ds_read_b128 v[146:149], v239 offset:256
	ds_read_b128 v[150:153], v239 offset:12544
	ds_read_b128 v[230:233], v238 offset:12544
	ds_read_b128 v[234:237], v238 offset:256
	s_setprio 1
	s_waitcnt lgkmcnt(7)
	v_mfma_f32_32x32x16_bf16 v[82:97], v[154:157], v[122:125], v[82:97]
	s_waitcnt lgkmcnt(6)
	v_mfma_f32_32x32x16_bf16 v[66:81], v[158:161], v[122:125], v[66:81]
	s_waitcnt lgkmcnt(5)
	v_mfma_f32_32x32x16_bf16 v[82:97], v[220:223], v[126:129], v[82:97]
	s_waitcnt lgkmcnt(4)
	v_mfma_f32_32x32x16_bf16 v[66:81], v[224:227], v[126:129], v[66:81]
	s_setprio 0
	ds_read_b128 v[154:157], v240 offset:256
	ds_read_b128 v[158:161], v240 offset:12544
	ds_read_b128 v[220:223], v0 offset:256
	ds_read_b128 v[224:227], v0 offset:12544
	s_setprio 1
	s_waitcnt lgkmcnt(4)
	v_mfma_f32_32x32x16_bf16 v[82:97], v[234:237], v[130:133], v[82:97]
	v_mfma_f32_32x32x16_bf16 v[66:81], v[230:233], v[130:133], v[66:81]
	v_mfma_f32_32x32x16_bf16 v[82:97], v[146:149], v[134:137], v[82:97]
	v_mfma_f32_32x32x16_bf16 v[66:81], v[150:153], v[134:137], v[66:81]
	s_setprio 0
	s_setprio 1
	s_waitcnt lgkmcnt(3)
	v_mfma_f32_32x32x16_bf16 v[82:97], v[154:157], v[138:141], v[82:97]
	s_waitcnt lgkmcnt(2)
	v_mfma_f32_32x32x16_bf16 v[66:81], v[158:161], v[138:141], v[66:81]
	s_waitcnt lgkmcnt(1)
	v_mfma_f32_32x32x16_bf16 v[82:97], v[220:223], v[142:145], v[82:97]
	s_waitcnt lgkmcnt(0)
	v_mfma_f32_32x32x16_bf16 v[66:81], v[224:227], v[142:145], v[66:81]
	s_setprio 0
	v_add3_u32 v0, s15, v205, v206
	v_add3_u32 v239, v0, v207, v208
	v_add_u32_e32 v246, v239, v211
	v_add_u32_e32 v247, v239, v215
	v_add_u32_e32 v248, v239, v216
	v_add_u32_e32 v249, v239, v217
	ds_read_b64_tr_b16 v[146:147], v246 offset:24576
	ds_read_b64_tr_b16 v[148:149], v246 offset:26624
	ds_read_b64_tr_b16 v[150:151], v247 offset:24576
	ds_read_b64_tr_b16 v[152:153], v247 offset:26624
	ds_read_b64_tr_b16 v[154:155], v248 offset:24576
	ds_read_b64_tr_b16 v[156:157], v248 offset:26624
	ds_read_b64_tr_b16 v[158:159], v249 offset:24576
	ds_read_b64_tr_b16 v[160:161], v249 offset:26624
	s_cmp_le_i32 s55, s40
	s_cbranch_scc1 .Ln192_nomask
; template <int DK>
; DI void attn_pass(const AttnSrc& s, const int q0, const float sc, LAS unsigned char* lds, f32x16 (&O)[4]) {
;     ...
;       if (64 * t + 63 > qw0) {
;         const int qa = qw0 + r, kbase = 64 * t + 4 * h;
; #pragma unroll
;         for (int j = 0; j < 16; ++j) { const int kv = kbase + (j & 3) + 8 * (j >> 2); if (kv > qa) p0[j] = -INFINITY; if (kv + 32 > qa) p1[j] = -INFINITY; }
;       }
	v_add_u32_e32 v0, s55, v212
	v_subrev_u32_e32 v222, 31, v0
	v_subrev_u32_e32 v221, 63, v0
	v_cmp_le_i32_e32 vcc, v222, v167
	s_nop 1
	v_cndmask_b32_e32 v66, v201, v66, vcc
	v_cmp_lt_i32_e32 vcc, v221, v167
	s_nop 1
	v_cndmask_b32_e32 v83, v201, v83, vcc
	v_cmp_le_i32_e32 vcc, v221, v167
	v_subrev_u32_e32 v221, 30, v0
	s_nop 0
	v_cndmask_b32_e32 v82, v201, v82, vcc
	v_cmp_le_i32_e32 vcc, v221, v167
	v_subrev_u32_e32 v221, 61, v0
	s_nop 0
	v_cndmask_b32_e32 v67, v201, v67, vcc
	v_cmp_le_i32_e32 vcc, v221, v167
	v_subrev_u32_e32 v221, 29, v0
	s_nop 0
	v_cndmask_b32_e32 v84, v201, v84, vcc
	v_cmp_le_i32_e32 vcc, v221, v167
	v_subrev_u32_e32 v221, 60, v0
	s_nop 0
	v_cndmask_b32_e32 v68, v201, v68, vcc
	v_cmp_le_i32_e32 vcc, v221, v167
	v_subrev_u32_e32 v221, 28, v0
	s_nop 0
	v_cndmask_b32_e32 v85, v201, v85, vcc
	v_cmp_le_i32_e32 vcc, v221, v167
	v_subrev_u32_e32 v221, 55, v0
	s_nop 0
	v_cndmask_b32_e32 v69, v201, v69, vcc
	v_cmp_le_i32_e32 vcc, v221, v167
	v_subrev_u32_e32 v221, 23, v0
	s_nop 0
	v_cndmask_b32_e32 v86, v201, v86, vcc
	v_cmp_le_i32_e32 vcc, v221, v167
	v_subrev_u32_e32 v221, 54, v0
	s_nop 0
	v_cndmask_b32_e32 v70, v201, v70, vcc
	v_cmp_le_i32_e32 vcc, v221, v167
	v_subrev_u32_e32 v221, 22, v0
	s_nop 0
	v_cndmask_b32_e32 v87, v201, v87, vcc
	v_cmp_le_i32_e32 vcc, v221, v167
	v_subrev_u32_e32 v221, 53, v0
	s_nop 0
	v_cndmask_b32_e32 v71, v201, v71, vcc
	v_cmp_le_i32_e32 vcc, v221, v167
	v_subrev_u32_e32 v221, 21, v0
	s_nop 0
	v_cndmask_b32_e32 v88, v201, v88, vcc
	v_cmp_le_i32_e32 vcc, v221, v167
	v_subrev_u32_e32 v221, 52, v0
	s_nop 0
	v_cndmask_b32_e32 v72, v201, v72, vcc
	v_cmp_le_i32_e32 vcc, v221, v167
	v_subrev_u32_e32 v221, 20, v0
	s_nop 0
	v_cndmask_b32_e32 v89, v201, v89, vcc
	v_cmp_le_i32_e32 vcc, v221, v167
	v_subrev_u32_e32 v221, 47, v0
	s_nop 0
	v_cndmask_b32_e32 v73, v201, v73, vcc
	v_cmp_le_i32_e32 vcc, v221, v167
	v_add_u32_e32 v221, -15, v0
	s_nop 0
	v_cndmask_b32_e32 v90, v201, v90, vcc
	v_cmp_le_i32_e32 vcc, v221, v167
	v_subrev_u32_e32 v221, 46, v0
	s_nop 0
	v_cndmask_b32_e32 v74, v201, v74, vcc
	v_cmp_le_i32_e32 vcc, v221, v167
	v_add_u32_e32 v221, -14, v0
	s_nop 0
	v_cndmask_b32_e32 v91, v201, v91, vcc
	v_cmp_le_i32_e32 vcc, v221, v167
	v_subrev_u32_e32 v221, 45, v0
	s_nop 0
	v_cndmask_b32_e32 v75, v201, v75, vcc
	v_cmp_le_i32_e32 vcc, v221, v167
	v_add_u32_e32 v221, -13, v0
	s_nop 0
	v_cndmask_b32_e32 v92, v201, v92, vcc
	v_cmp_le_i32_e32 vcc, v221, v167
	v_subrev_u32_e32 v221, 44, v0
	s_nop 0
	v_cndmask_b32_e32 v76, v201, v76, vcc
	v_cmp_le_i32_e32 vcc, v221, v167
	v_add_u32_e32 v221, -12, v0
	s_nop 0
	v_cndmask_b32_e32 v93, v201, v93, vcc
	v_cmp_le_i32_e32 vcc, v221, v167
	v_subrev_u32_e32 v221, 39, v0
	s_nop 0
	v_cndmask_b32_e32 v77, v201, v77, vcc
	v_cmp_le_i32_e32 vcc, v221, v167
	v_add_u32_e32 v221, -7, v0
	s_nop 0
	v_cndmask_b32_e32 v94, v201, v94, vcc
	v_cmp_le_i32_e32 vcc, v221, v167
	v_subrev_u32_e32 v221, 38, v0
	s_nop 0
	v_cndmask_b32_e32 v78, v201, v78, vcc
	v_cmp_le_i32_e32 vcc, v221, v167
	v_add_u32_e32 v221, -6, v0
	s_nop 0
	v_cndmask_b32_e32 v95, v201, v95, vcc
	v_cmp_le_i32_e32 vcc, v221, v167
	v_subrev_u32_e32 v221, 37, v0
	s_nop 0
	v_cndmask_b32_e32 v79, v201, v79, vcc
	v_cmp_le_i32_e32 vcc, v221, v167
	v_add_u32_e32 v221, -5, v0
	s_nop 0
	v_cndmask_b32_e32 v96, v201, v96, vcc
	v_cmp_le_i32_e32 vcc, v221, v167
	v_subrev_u32_e32 v221, 36, v0
	v_add_u32_e32 v0, -4, v0
	v_cndmask_b32_e32 v80, v201, v80, vcc
	v_cmp_le_i32_e32 vcc, v221, v167
	s_nop 1
	v_cndmask_b32_e32 v97, v201, v97, vcc
	v_cmp_le_i32_e32 vcc, v0, v167
	s_nop 1
	v_cndmask_b32_e32 v81, v201, v81, vcc
